# rows passes kinds 1,2: nt hint on read-once x/Y loads and x f32 stores (H stores stay cacheable)
# baseline (speedup 1.0000x reference)
.Lrows_common:
	s_lshl_b32 s0, s45, 11
	s_add_u32 s38, s14, s0
	s_addc_u32 s39, s15, 0
	s_add_u32 s40, s12, s0
	s_addc_u32 s41, s13, 0
	s_lshl_b32 s42, s46, 12
	v_add_u32_e32 v5, s42, v3
	global_load_dwordx2 v[74:75], v4, s[38:39] nt
	global_load_dwordx2 v[76:77], v4, s[38:39] offset:512 nt
	global_load_dwordx2 v[78:79], v4, s[38:39] offset:1024 nt
	global_load_dwordx2 v[80:81], v4, s[38:39] offset:1536 nt
	s_add_u32 s38, s38, 0x800
	s_addc_u32 s39, s39, 0
	global_load_dwordx2 v[82:83], v4, s[38:39] nt
	global_load_dwordx2 v[84:85], v4, s[38:39] offset:512 nt
	global_load_dwordx2 v[86:87], v4, s[38:39] offset:1024 nt
	global_load_dwordx2 v[88:89], v4, s[38:39] offset:1536 nt
	s_add_u32 s38, s38, 0x800
	s_addc_u32 s39, s39, 0
	global_load_dwordx2 v[90:91], v4, s[38:39] nt
	global_load_dwordx2 v[92:93], v4, s[38:39] offset:512 nt
	global_load_dwordx2 v[94:95], v4, s[38:39] offset:1024 nt
	global_load_dwordx2 v[96:97], v4, s[38:39] offset:1536 nt
	s_add_u32 s38, s38, 0x800
	s_addc_u32 s39, s39, 0
	global_load_dwordx2 v[98:99], v4, s[38:39] nt
	global_load_dwordx2 v[100:101], v4, s[38:39] offset:512 nt
	global_load_dwordx2 v[102:103], v4, s[38:39] offset:1024 nt
	global_load_dwordx2 v[104:105], v4, s[38:39] offset:1536 nt
	global_load_dwordx4 v[10:13], v3, s[24:25] nt
	global_load_dwordx4 v[14:17], v3, s[24:25] offset:1024 nt
	global_load_dwordx4 v[18:21], v3, s[24:25] offset:2048 nt
	global_load_dwordx4 v[22:25], v3, s[24:25] offset:3072 nt
	s_add_u32 s24, s24, 0x1000
	s_addc_u32 s25, s25, 0
	global_load_dwordx4 v[26:29], v3, s[24:25] nt
	global_load_dwordx4 v[30:33], v3, s[24:25] offset:1024 nt
	global_load_dwordx4 v[34:37], v3, s[24:25] offset:2048 nt
	global_load_dwordx4 v[38:41], v3, s[24:25] offset:3072 nt
	s_add_u32 s24, s24, 0x1000
	s_addc_u32 s25, s25, 0
	global_load_dwordx4 v[42:45], v3, s[24:25] nt
	global_load_dwordx4 v[46:49], v3, s[24:25] offset:1024 nt
	global_load_dwordx4 v[50:53], v3, s[24:25] offset:2048 nt
	global_load_dwordx4 v[54:57], v3, s[24:25] offset:3072 nt
	s_add_u32 s24, s24, 0x1000
	s_addc_u32 s25, s25, 0
	global_load_dwordx4 v[58:61], v3, s[24:25] nt
	global_load_dwordx4 v[62:65], v3, s[24:25] offset:1024 nt
	global_load_dwordx4 v[66:69], v3, s[24:25] offset:2048 nt
	global_load_dwordx4 v[70:73], v3, s[24:25] offset:3072 nt
	s_waitcnt vmcnt(16)
	v_lshlrev_b32_e32 v122, 16, v74
	v_and_b32_e32 v123, 0xffff0000, v74
	v_lshlrev_b32_e32 v124, 16, v82
	v_and_b32_e32 v125, 0xffff0000, v82
	v_lshlrev_b32_e32 v126, 16, v90
	v_and_b32_e32 v127, 0xffff0000, v90
	v_lshlrev_b32_e32 v128, 16, v98
	v_and_b32_e32 v129, 0xffff0000, v98
	v_pk_mul_f32 v[132:133], v[122:123], v[122:123]
	v_pk_mul_f32 v[134:135], v[124:125], v[124:125]
	v_pk_mul_f32 v[136:137], v[126:127], v[126:127]
	v_pk_mul_f32 v[138:139], v[128:129], v[128:129]
	v_add_f32_e32 v106, v132, v133
	v_add_f32_e32 v107, v134, v135
	v_add_f32_e32 v108, v136, v137
	v_add_f32_e32 v109, v138, v139
	v_lshlrev_b32_e32 v122, 16, v75
	v_and_b32_e32 v123, 0xffff0000, v75
	v_lshlrev_b32_e32 v124, 16, v83
	v_and_b32_e32 v125, 0xffff0000, v83
	v_lshlrev_b32_e32 v126, 16, v91
	v_and_b32_e32 v127, 0xffff0000, v91
	v_lshlrev_b32_e32 v128, 16, v99
	v_and_b32_e32 v129, 0xffff0000, v99
	v_pk_mul_f32 v[132:133], v[122:123], v[122:123]
	v_pk_mul_f32 v[134:135], v[124:125], v[124:125]
	v_pk_mul_f32 v[136:137], v[126:127], v[126:127]
	v_pk_mul_f32 v[138:139], v[128:129], v[128:129]
	v_add_f32_e32 v106, v106, v132
	v_add_f32_e32 v107, v107, v134
	v_add_f32_e32 v108, v108, v136
	v_add_f32_e32 v109, v109, v138
	v_add_f32_e32 v106, v133, v106
	v_add_f32_e32 v107, v135, v107
	v_add_f32_e32 v108, v137, v108
	v_add_f32_e32 v109, v139, v109
	v_lshlrev_b32_e32 v122, 16, v76
	v_and_b32_e32 v123, 0xffff0000, v76
	v_lshlrev_b32_e32 v124, 16, v84
	v_and_b32_e32 v125, 0xffff0000, v84
	v_lshlrev_b32_e32 v126, 16, v92
	v_and_b32_e32 v127, 0xffff0000, v92
	v_lshlrev_b32_e32 v128, 16, v100
	v_and_b32_e32 v129, 0xffff0000, v100
	v_pk_mul_f32 v[132:133], v[122:123], v[122:123]
	v_pk_mul_f32 v[134:135], v[124:125], v[124:125]
	v_pk_mul_f32 v[136:137], v[126:127], v[126:127]
	v_pk_mul_f32 v[138:139], v[128:129], v[128:129]
	v_add_f32_e32 v106, v106, v132
	v_add_f32_e32 v107, v107, v134
	v_add_f32_e32 v108, v108, v136
	v_add_f32_e32 v109, v109, v138
	v_add_f32_e32 v106, v133, v106
	v_add_f32_e32 v107, v135, v107
	v_add_f32_e32 v108, v137, v108
	v_add_f32_e32 v109, v139, v109
	v_lshlrev_b32_e32 v122, 16, v77
	v_and_b32_e32 v123, 0xffff0000, v77
	v_lshlrev_b32_e32 v124, 16, v85
	v_and_b32_e32 v125, 0xffff0000, v85
	v_lshlrev_b32_e32 v126, 16, v93
	v_and_b32_e32 v127, 0xffff0000, v93
	v_lshlrev_b32_e32 v128, 16, v101
	v_and_b32_e32 v129, 0xffff0000, v101
	v_pk_mul_f32 v[132:133], v[122:123], v[122:123]
	v_pk_mul_f32 v[134:135], v[124:125], v[124:125]
	v_pk_mul_f32 v[136:137], v[126:127], v[126:127]
	v_pk_mul_f32 v[138:139], v[128:129], v[128:129]
	v_add_f32_e32 v106, v106, v132
	v_add_f32_e32 v107, v107, v134
	v_add_f32_e32 v108, v108, v136
	v_add_f32_e32 v109, v109, v138
	v_add_f32_e32 v106, v133, v106
	v_add_f32_e32 v107, v135, v107
	v_add_f32_e32 v108, v137, v108
	v_add_f32_e32 v109, v139, v109
	v_lshlrev_b32_e32 v122, 16, v78
	v_and_b32_e32 v123, 0xffff0000, v78
	v_lshlrev_b32_e32 v124, 16, v86
	v_and_b32_e32 v125, 0xffff0000, v86
	v_lshlrev_b32_e32 v126, 16, v94
	v_and_b32_e32 v127, 0xffff0000, v94
	v_lshlrev_b32_e32 v128, 16, v102
	v_and_b32_e32 v129, 0xffff0000, v102
	v_pk_mul_f32 v[132:133], v[122:123], v[122:123]
	v_pk_mul_f32 v[134:135], v[124:125], v[124:125]
	v_pk_mul_f32 v[136:137], v[126:127], v[126:127]
	v_pk_mul_f32 v[138:139], v[128:129], v[128:129]
	v_add_f32_e32 v106, v106, v132
	v_add_f32_e32 v107, v107, v134
	v_add_f32_e32 v108, v108, v136
	v_add_f32_e32 v109, v109, v138
	v_add_f32_e32 v106, v133, v106
	v_add_f32_e32 v107, v135, v107
	v_add_f32_e32 v108, v137, v108
	v_add_f32_e32 v109, v139, v109
	v_lshlrev_b32_e32 v122, 16, v79
	v_and_b32_e32 v123, 0xffff0000, v79
	v_lshlrev_b32_e32 v124, 16, v87
	v_and_b32_e32 v125, 0xffff0000, v87
	v_lshlrev_b32_e32 v126, 16, v95
	v_and_b32_e32 v127, 0xffff0000, v95
	v_lshlrev_b32_e32 v128, 16, v103
	v_and_b32_e32 v129, 0xffff0000, v103
	v_pk_mul_f32 v[132:133], v[122:123], v[122:123]
	v_pk_mul_f32 v[134:135], v[124:125], v[124:125]
	v_pk_mul_f32 v[136:137], v[126:127], v[126:127]
	v_pk_mul_f32 v[138:139], v[128:129], v[128:129]
	v_add_f32_e32 v106, v106, v132
	v_add_f32_e32 v107, v107, v134
	v_add_f32_e32 v108, v108, v136
	v_add_f32_e32 v109, v109, v138
	v_add_f32_e32 v106, v133, v106
	v_add_f32_e32 v107, v135, v107
	v_add_f32_e32 v108, v137, v108
	v_add_f32_e32 v109, v139, v109
	v_lshlrev_b32_e32 v122, 16, v80
	v_and_b32_e32 v123, 0xffff0000, v80
	v_lshlrev_b32_e32 v124, 16, v88
	v_and_b32_e32 v125, 0xffff0000, v88
	v_lshlrev_b32_e32 v126, 16, v96
	v_and_b32_e32 v127, 0xffff0000, v96
	v_lshlrev_b32_e32 v128, 16, v104
	v_and_b32_e32 v129, 0xffff0000, v104
	v_pk_mul_f32 v[132:133], v[122:123], v[122:123]
	v_pk_mul_f32 v[134:135], v[124:125], v[124:125]
	v_pk_mul_f32 v[136:137], v[126:127], v[126:127]
	v_pk_mul_f32 v[138:139], v[128:129], v[128:129]
	v_add_f32_e32 v106, v106, v132
	v_add_f32_e32 v107, v107, v134
	v_add_f32_e32 v108, v108, v136
	v_add_f32_e32 v109, v109, v138
	v_add_f32_e32 v106, v133, v106
	v_add_f32_e32 v107, v135, v107
	v_add_f32_e32 v108, v137, v108
	v_add_f32_e32 v109, v139, v109
	v_lshlrev_b32_e32 v122, 16, v81
	v_and_b32_e32 v123, 0xffff0000, v81
	v_lshlrev_b32_e32 v124, 16, v89
	v_and_b32_e32 v125, 0xffff0000, v89
	v_lshlrev_b32_e32 v126, 16, v97
	v_and_b32_e32 v127, 0xffff0000, v97
	v_lshlrev_b32_e32 v128, 16, v105
	v_and_b32_e32 v129, 0xffff0000, v105
	v_pk_mul_f32 v[132:133], v[122:123], v[122:123]
	v_pk_mul_f32 v[134:135], v[124:125], v[124:125]
	v_pk_mul_f32 v[136:137], v[126:127], v[126:127]
	v_pk_mul_f32 v[138:139], v[128:129], v[128:129]
	v_add_f32_e32 v106, v106, v132
	v_add_f32_e32 v107, v107, v134
	v_add_f32_e32 v108, v108, v136
	v_add_f32_e32 v109, v109, v138
	v_add_f32_e32 v106, v133, v106
	v_add_f32_e32 v107, v135, v107
	v_add_f32_e32 v108, v137, v108
	v_add_f32_e32 v109, v139, v109
	v_mov_b32_e32 v110, v106
	v_mov_b32_e32 v111, v107
	v_mov_b32_e32 v112, v108
	v_mov_b32_e32 v113, v109
	v_permlane32_swap_b32_e32 v106, v110
	v_permlane32_swap_b32_e32 v107, v111
	v_permlane32_swap_b32_e32 v108, v112
	v_permlane32_swap_b32_e32 v109, v113
	v_add_f32_e32 v106, v106, v110
	v_add_f32_e32 v107, v107, v111
	v_add_f32_e32 v108, v108, v112
	v_add_f32_e32 v109, v109, v113
	v_mov_b32_e32 v110, v106
	v_mov_b32_e32 v111, v107
	v_mov_b32_e32 v112, v108
	v_mov_b32_e32 v113, v109
	v_permlane16_swap_b32_e32 v106, v110
	v_permlane16_swap_b32_e32 v107, v111
	v_permlane16_swap_b32_e32 v108, v112
	v_permlane16_swap_b32_e32 v109, v113
	v_add_f32_e32 v106, v106, v110
	v_add_f32_e32 v107, v107, v111
	v_add_f32_e32 v108, v108, v112
	v_add_f32_e32 v109, v109, v113
	v_add_f32_dpp v106, v106, v106 row_ror:8 row_mask:0xf bank_mask:0xf
	v_add_f32_dpp v107, v107, v107 row_ror:8 row_mask:0xf bank_mask:0xf
	v_add_f32_dpp v108, v108, v108 row_ror:8 row_mask:0xf bank_mask:0xf
	v_add_f32_dpp v109, v109, v109 row_ror:8 row_mask:0xf bank_mask:0xf
	v_add_f32_dpp v110, v106, v106 row_shl:4 row_mask:0xf bank_mask:0x5
	v_add_f32_dpp v111, v107, v107 row_shl:4 row_mask:0xf bank_mask:0x5
	v_add_f32_dpp v112, v108, v108 row_shl:4 row_mask:0xf bank_mask:0x5
	v_add_f32_dpp v113, v109, v109 row_shl:4 row_mask:0xf bank_mask:0x5
	v_add_f32_dpp v110, v106, v106 row_shr:4 row_mask:0xf bank_mask:0xa
	v_add_f32_dpp v111, v107, v107 row_shr:4 row_mask:0xf bank_mask:0xa
	v_add_f32_dpp v112, v108, v108 row_shr:4 row_mask:0xf bank_mask:0xa
	v_add_f32_dpp v113, v109, v109 row_shr:4 row_mask:0xf bank_mask:0xa
	v_add_f32_dpp v106, v110, v110 quad_perm:[2,3,0,1] row_mask:0xf bank_mask:0xf
	v_add_f32_dpp v107, v111, v111 quad_perm:[2,3,0,1] row_mask:0xf bank_mask:0xf
	v_add_f32_dpp v108, v112, v112 quad_perm:[2,3,0,1] row_mask:0xf bank_mask:0xf
	v_add_f32_dpp v109, v113, v113 quad_perm:[2,3,0,1] row_mask:0xf bank_mask:0xf
	v_add_f32_dpp v110, v106, v106 quad_perm:[1,0,3,2] row_mask:0xf bank_mask:0xf
	v_add_f32_dpp v111, v107, v107 quad_perm:[1,0,3,2] row_mask:0xf bank_mask:0xf
	v_add_f32_dpp v112, v108, v108 quad_perm:[1,0,3,2] row_mask:0xf bank_mask:0xf
	v_add_f32_dpp v113, v109, v109 quad_perm:[1,0,3,2] row_mask:0xf bank_mask:0xf
	v_fmamk_f32 v110, v110, 0x3a800000, v198
	v_fmamk_f32 v111, v111, 0x3a800000, v198
	v_fmamk_f32 v112, v112, 0x3a800000, v198
	v_fmamk_f32 v113, v113, 0x3a800000, v198
	v_rsq_f32_e32 v114, v110
	v_rsq_f32_e32 v116, v111
	v_rsq_f32_e32 v118, v112
	v_rsq_f32_e32 v120, v113
	ds_read_b128 v[140:143], v5 offset:0
	ds_read_b128 v[144:147], v6 offset:0
	s_waitcnt vmcnt(12)
	v_lshlrev_b32_e32 v122, 16, v74
	v_and_b32_e32 v123, 0xffff0000, v74
	v_lshlrev_b32_e32 v124, 16, v75
	v_and_b32_e32 v125, 0xffff0000, v75
	s_waitcnt lgkmcnt(0)
	v_pk_mul_f32 v[122:123], v[114:115], v[122:123] op_sel_hi:[0,1]
	v_pk_mul_f32 v[124:125], v[114:115], v[124:125] op_sel_hi:[0,1]
	v_pk_mul_f32 v[122:123], v[144:145], v[122:123]
	v_pk_mul_f32 v[124:125], v[146:147], v[124:125]
	v_pk_fma_f32 v[10:11], v[140:141], v[122:123], v[10:11]
	v_pk_fma_f32 v[12:13], v[142:143], v[124:125], v[12:13]
	s_waitcnt vmcnt(8)
	v_lshlrev_b32_e32 v122, 16, v82
	v_and_b32_e32 v123, 0xffff0000, v82
	v_lshlrev_b32_e32 v124, 16, v83
	v_and_b32_e32 v125, 0xffff0000, v83
	v_pk_mul_f32 v[122:123], v[116:117], v[122:123] op_sel_hi:[0,1]
	v_pk_mul_f32 v[124:125], v[116:117], v[124:125] op_sel_hi:[0,1]
	v_pk_mul_f32 v[122:123], v[144:145], v[122:123]
	v_pk_mul_f32 v[124:125], v[146:147], v[124:125]
	v_pk_fma_f32 v[26:27], v[140:141], v[122:123], v[26:27]
	v_pk_fma_f32 v[28:29], v[142:143], v[124:125], v[28:29]
	s_waitcnt vmcnt(4)
	v_lshlrev_b32_e32 v122, 16, v90
	v_and_b32_e32 v123, 0xffff0000, v90
	v_lshlrev_b32_e32 v124, 16, v91
	v_and_b32_e32 v125, 0xffff0000, v91
	v_pk_mul_f32 v[122:123], v[118:119], v[122:123] op_sel_hi:[0,1]
	v_pk_mul_f32 v[124:125], v[118:119], v[124:125] op_sel_hi:[0,1]
	v_pk_mul_f32 v[122:123], v[144:145], v[122:123]
	v_pk_mul_f32 v[124:125], v[146:147], v[124:125]
	v_pk_fma_f32 v[42:43], v[140:141], v[122:123], v[42:43]
	v_pk_fma_f32 v[44:45], v[142:143], v[124:125], v[44:45]
	s_waitcnt vmcnt(0)
	v_lshlrev_b32_e32 v122, 16, v98
	v_and_b32_e32 v123, 0xffff0000, v98
	v_lshlrev_b32_e32 v124, 16, v99
	v_and_b32_e32 v125, 0xffff0000, v99
	v_pk_mul_f32 v[122:123], v[120:121], v[122:123] op_sel_hi:[0,1]
	v_pk_mul_f32 v[124:125], v[120:121], v[124:125] op_sel_hi:[0,1]
	v_pk_mul_f32 v[122:123], v[144:145], v[122:123]
	v_pk_mul_f32 v[124:125], v[146:147], v[124:125]
	v_pk_fma_f32 v[58:59], v[140:141], v[122:123], v[58:59]
	v_pk_fma_f32 v[60:61], v[142:143], v[124:125], v[60:61]
	ds_read_b128 v[140:143], v5 offset:1024
	ds_read_b128 v[144:147], v6 offset:1024
	v_lshlrev_b32_e32 v122, 16, v76
	v_and_b32_e32 v123, 0xffff0000, v76
	v_lshlrev_b32_e32 v124, 16, v77
	v_and_b32_e32 v125, 0xffff0000, v77
	s_waitcnt lgkmcnt(0)
	v_pk_mul_f32 v[122:123], v[114:115], v[122:123] op_sel_hi:[0,1]
	v_pk_mul_f32 v[124:125], v[114:115], v[124:125] op_sel_hi:[0,1]
	v_pk_mul_f32 v[122:123], v[144:145], v[122:123]
	v_pk_mul_f32 v[124:125], v[146:147], v[124:125]
	v_pk_fma_f32 v[14:15], v[140:141], v[122:123], v[14:15]
	v_pk_fma_f32 v[16:17], v[142:143], v[124:125], v[16:17]
	v_lshlrev_b32_e32 v122, 16, v84
	v_and_b32_e32 v123, 0xffff0000, v84
	v_lshlrev_b32_e32 v124, 16, v85
	v_and_b32_e32 v125, 0xffff0000, v85
	v_pk_mul_f32 v[122:123], v[116:117], v[122:123] op_sel_hi:[0,1]
	v_pk_mul_f32 v[124:125], v[116:117], v[124:125] op_sel_hi:[0,1]
	v_pk_mul_f32 v[122:123], v[144:145], v[122:123]
	v_pk_mul_f32 v[124:125], v[146:147], v[124:125]
	v_pk_fma_f32 v[30:31], v[140:141], v[122:123], v[30:31]
	v_pk_fma_f32 v[32:33], v[142:143], v[124:125], v[32:33]
	v_lshlrev_b32_e32 v122, 16, v92
	v_and_b32_e32 v123, 0xffff0000, v92
	v_lshlrev_b32_e32 v124, 16, v93
	v_and_b32_e32 v125, 0xffff0000, v93
	v_pk_mul_f32 v[122:123], v[118:119], v[122:123] op_sel_hi:[0,1]
	v_pk_mul_f32 v[124:125], v[118:119], v[124:125] op_sel_hi:[0,1]
	v_pk_mul_f32 v[122:123], v[144:145], v[122:123]
	v_pk_mul_f32 v[124:125], v[146:147], v[124:125]
	v_pk_fma_f32 v[46:47], v[140:141], v[122:123], v[46:47]
	v_pk_fma_f32 v[48:49], v[142:143], v[124:125], v[48:49]
	v_lshlrev_b32_e32 v122, 16, v100
	v_and_b32_e32 v123, 0xffff0000, v100
	v_lshlrev_b32_e32 v124, 16, v101
	v_and_b32_e32 v125, 0xffff0000, v101
	v_pk_mul_f32 v[122:123], v[120:121], v[122:123] op_sel_hi:[0,1]
	v_pk_mul_f32 v[124:125], v[120:121], v[124:125] op_sel_hi:[0,1]
	v_pk_mul_f32 v[122:123], v[144:145], v[122:123]
	v_pk_mul_f32 v[124:125], v[146:147], v[124:125]
	v_pk_fma_f32 v[62:63], v[140:141], v[122:123], v[62:63]
	v_pk_fma_f32 v[64:65], v[142:143], v[124:125], v[64:65]
	ds_read_b128 v[140:143], v5 offset:2048
	ds_read_b128 v[144:147], v6 offset:2048
	v_lshlrev_b32_e32 v122, 16, v78
	v_and_b32_e32 v123, 0xffff0000, v78
	v_lshlrev_b32_e32 v124, 16, v79
	v_and_b32_e32 v125, 0xffff0000, v79
	s_waitcnt lgkmcnt(0)
	v_pk_mul_f32 v[122:123], v[114:115], v[122:123] op_sel_hi:[0,1]
	v_pk_mul_f32 v[124:125], v[114:115], v[124:125] op_sel_hi:[0,1]
	v_pk_mul_f32 v[122:123], v[144:145], v[122:123]
	v_pk_mul_f32 v[124:125], v[146:147], v[124:125]
	v_pk_fma_f32 v[18:19], v[140:141], v[122:123], v[18:19]
	v_pk_fma_f32 v[20:21], v[142:143], v[124:125], v[20:21]
	v_lshlrev_b32_e32 v122, 16, v86
	v_and_b32_e32 v123, 0xffff0000, v86
	v_lshlrev_b32_e32 v124, 16, v87
	v_and_b32_e32 v125, 0xffff0000, v87
	v_pk_mul_f32 v[122:123], v[116:117], v[122:123] op_sel_hi:[0,1]
	v_pk_mul_f32 v[124:125], v[116:117], v[124:125] op_sel_hi:[0,1]
	v_pk_mul_f32 v[122:123], v[144:145], v[122:123]
	v_pk_mul_f32 v[124:125], v[146:147], v[124:125]
	v_pk_fma_f32 v[34:35], v[140:141], v[122:123], v[34:35]
	v_pk_fma_f32 v[36:37], v[142:143], v[124:125], v[36:37]
	v_lshlrev_b32_e32 v122, 16, v94
	v_and_b32_e32 v123, 0xffff0000, v94
	v_lshlrev_b32_e32 v124, 16, v95
	v_and_b32_e32 v125, 0xffff0000, v95
	v_pk_mul_f32 v[122:123], v[118:119], v[122:123] op_sel_hi:[0,1]
	v_pk_mul_f32 v[124:125], v[118:119], v[124:125] op_sel_hi:[0,1]
	v_pk_mul_f32 v[122:123], v[144:145], v[122:123]
	v_pk_mul_f32 v[124:125], v[146:147], v[124:125]
	v_pk_fma_f32 v[50:51], v[140:141], v[122:123], v[50:51]
	v_pk_fma_f32 v[52:53], v[142:143], v[124:125], v[52:53]
	v_lshlrev_b32_e32 v122, 16, v102
	v_and_b32_e32 v123, 0xffff0000, v102
	v_lshlrev_b32_e32 v124, 16, v103
	v_and_b32_e32 v125, 0xffff0000, v103
	v_pk_mul_f32 v[122:123], v[120:121], v[122:123] op_sel_hi:[0,1]
	v_pk_mul_f32 v[124:125], v[120:121], v[124:125] op_sel_hi:[0,1]
	v_pk_mul_f32 v[122:123], v[144:145], v[122:123]
	v_pk_mul_f32 v[124:125], v[146:147], v[124:125]
	v_pk_fma_f32 v[66:67], v[140:141], v[122:123], v[66:67]
	v_pk_fma_f32 v[68:69], v[142:143], v[124:125], v[68:69]
	ds_read_b128 v[140:143], v5 offset:3072
	ds_read_b128 v[144:147], v6 offset:3072
	v_lshlrev_b32_e32 v122, 16, v80
	v_and_b32_e32 v123, 0xffff0000, v80
	v_lshlrev_b32_e32 v124, 16, v81
	v_and_b32_e32 v125, 0xffff0000, v81
	s_waitcnt lgkmcnt(0)
	v_pk_mul_f32 v[122:123], v[114:115], v[122:123] op_sel_hi:[0,1]
	v_pk_mul_f32 v[124:125], v[114:115], v[124:125] op_sel_hi:[0,1]
	v_pk_mul_f32 v[122:123], v[144:145], v[122:123]
	v_pk_mul_f32 v[124:125], v[146:147], v[124:125]
	v_pk_fma_f32 v[22:23], v[140:141], v[122:123], v[22:23]
	v_pk_fma_f32 v[24:25], v[142:143], v[124:125], v[24:25]
	v_lshlrev_b32_e32 v122, 16, v88
	v_and_b32_e32 v123, 0xffff0000, v88
	v_lshlrev_b32_e32 v124, 16, v89
	v_and_b32_e32 v125, 0xffff0000, v89
	v_pk_mul_f32 v[122:123], v[116:117], v[122:123] op_sel_hi:[0,1]
	v_pk_mul_f32 v[124:125], v[116:117], v[124:125] op_sel_hi:[0,1]
	v_pk_mul_f32 v[122:123], v[144:145], v[122:123]
	v_pk_mul_f32 v[124:125], v[146:147], v[124:125]
	v_pk_fma_f32 v[38:39], v[140:141], v[122:123], v[38:39]
	v_pk_fma_f32 v[40:41], v[142:143], v[124:125], v[40:41]
	v_lshlrev_b32_e32 v122, 16, v96
	v_and_b32_e32 v123, 0xffff0000, v96
	v_lshlrev_b32_e32 v124, 16, v97
	v_and_b32_e32 v125, 0xffff0000, v97
	v_pk_mul_f32 v[122:123], v[118:119], v[122:123] op_sel_hi:[0,1]
	v_pk_mul_f32 v[124:125], v[118:119], v[124:125] op_sel_hi:[0,1]
	v_pk_mul_f32 v[122:123], v[144:145], v[122:123]
	v_pk_mul_f32 v[124:125], v[146:147], v[124:125]
	v_pk_fma_f32 v[54:55], v[140:141], v[122:123], v[54:55]
	v_pk_fma_f32 v[56:57], v[142:143], v[124:125], v[56:57]
	v_lshlrev_b32_e32 v122, 16, v104
	v_and_b32_e32 v123, 0xffff0000, v104
	v_lshlrev_b32_e32 v124, 16, v105
	v_and_b32_e32 v125, 0xffff0000, v105
	v_pk_mul_f32 v[122:123], v[120:121], v[122:123] op_sel_hi:[0,1]
	v_pk_mul_f32 v[124:125], v[120:121], v[124:125] op_sel_hi:[0,1]
	v_pk_mul_f32 v[122:123], v[144:145], v[122:123]
	v_pk_mul_f32 v[124:125], v[146:147], v[124:125]
	v_pk_fma_f32 v[70:71], v[140:141], v[122:123], v[70:71]
	v_pk_fma_f32 v[72:73], v[142:143], v[124:125], v[72:73]
	global_store_dwordx4 v3, v[10:13], s[26:27] nt
	global_store_dwordx4 v3, v[14:17], s[26:27] offset:1024 nt
	global_store_dwordx4 v3, v[18:21], s[26:27] offset:2048 nt
	global_store_dwordx4 v3, v[22:25], s[26:27] offset:3072 nt
	s_add_u32 s26, s26, 0x1000
	s_addc_u32 s27, s27, 0
	global_store_dwordx4 v3, v[26:29], s[26:27] nt
	global_store_dwordx4 v3, v[30:33], s[26:27] offset:1024 nt
	global_store_dwordx4 v3, v[34:37], s[26:27] offset:2048 nt
	global_store_dwordx4 v3, v[38:41], s[26:27] offset:3072 nt
	s_add_u32 s26, s26, 0x1000
	s_addc_u32 s27, s27, 0
	global_store_dwordx4 v3, v[42:45], s[26:27] nt
	global_store_dwordx4 v3, v[46:49], s[26:27] offset:1024 nt
	global_store_dwordx4 v3, v[50:53], s[26:27] offset:2048 nt
	global_store_dwordx4 v3, v[54:57], s[26:27] offset:3072 nt
	s_add_u32 s26, s26, 0x1000
	s_addc_u32 s27, s27, 0
	global_store_dwordx4 v3, v[58:61], s[26:27] nt
	global_store_dwordx4 v3, v[62:65], s[26:27] offset:1024 nt
	global_store_dwordx4 v3, v[66:69], s[26:27] offset:2048 nt
	global_store_dwordx4 v3, v[70:73], s[26:27] offset:3072 nt
	s_bitcmp1_b32 s43, 0
	s_cbranch_scc0 .Lrows_next
	v_mul_f32_e32 v122, v11, v11
	v_mul_f32_e32 v126, v27, v27
	v_mul_f32_e32 v132, v43, v43
	v_mul_f32_e32 v136, v59, v59
	v_fma_f32 v122, v10, v10, v122
	v_fma_f32 v126, v26, v26, v126
	v_fma_f32 v132, v42, v42, v132
	v_fma_f32 v136, v58, v58, v136
	v_fma_f32 v122, v12, v12, v122
	v_fma_f32 v126, v28, v28, v126
	v_fma_f32 v132, v44, v44, v132
	v_fma_f32 v136, v60, v60, v136
	v_fma_f32 v122, v13, v13, v122
	v_fma_f32 v126, v29, v29, v126
	v_fma_f32 v132, v45, v45, v132
	v_fma_f32 v136, v61, v61, v136
	v_mul_f32_e32 v123, v15, v15
	v_mul_f32_e32 v127, v31, v31
	v_mul_f32_e32 v133, v47, v47
	v_mul_f32_e32 v137, v63, v63
	v_fma_f32 v123, v14, v14, v123
	v_fma_f32 v127, v30, v30, v127
	v_fma_f32 v133, v46, v46, v133
	v_fma_f32 v137, v62, v62, v137
	v_fma_f32 v123, v16, v16, v123
	v_fma_f32 v127, v32, v32, v127
	v_fma_f32 v133, v48, v48, v133
	v_fma_f32 v137, v64, v64, v137
	v_fma_f32 v123, v17, v17, v123
	v_fma_f32 v127, v33, v33, v127
	v_fma_f32 v133, v49, v49, v133
	v_fma_f32 v137, v65, v65, v137
	v_mul_f32_e32 v124, v19, v19
	v_mul_f32_e32 v128, v35, v35
	v_mul_f32_e32 v134, v51, v51
	v_mul_f32_e32 v138, v67, v67
	v_fma_f32 v124, v18, v18, v124
	v_fma_f32 v128, v34, v34, v128
	v_fma_f32 v134, v50, v50, v134
	v_fma_f32 v138, v66, v66, v138
	v_fma_f32 v124, v20, v20, v124
	v_fma_f32 v128, v36, v36, v128
	v_fma_f32 v134, v52, v52, v134
	v_fma_f32 v138, v68, v68, v138
	v_fma_f32 v124, v21, v21, v124
	v_fma_f32 v128, v37, v37, v128
	v_fma_f32 v134, v53, v53, v134
	v_fma_f32 v138, v69, v69, v138
	v_mul_f32_e32 v125, v23, v23
	v_mul_f32_e32 v129, v39, v39
	v_mul_f32_e32 v135, v55, v55
	v_mul_f32_e32 v139, v71, v71
	v_fma_f32 v125, v22, v22, v125
	v_fma_f32 v129, v38, v38, v129
	v_fma_f32 v135, v54, v54, v135
	v_fma_f32 v139, v70, v70, v139
	v_fma_f32 v125, v24, v24, v125
	v_fma_f32 v129, v40, v40, v129
	v_fma_f32 v135, v56, v56, v135
	v_fma_f32 v139, v72, v72, v139
	v_fma_f32 v125, v25, v25, v125
	v_fma_f32 v129, v41, v41, v129
	v_fma_f32 v135, v57, v57, v135
	v_fma_f32 v139, v73, v73, v139
	v_add_f32_e32 v106, v122, v123
	v_add_f32_e32 v107, v126, v127
	v_add_f32_e32 v108, v132, v133
	v_add_f32_e32 v109, v136, v137
	v_add_f32_e32 v106, v106, v124
	v_add_f32_e32 v107, v107, v128
	v_add_f32_e32 v108, v108, v134
	v_add_f32_e32 v109, v109, v138
	v_add_f32_e32 v106, v106, v125
	v_add_f32_e32 v107, v107, v129
	v_add_f32_e32 v108, v108, v135
	v_add_f32_e32 v109, v109, v139
	v_mov_b32_e32 v110, v106
	v_mov_b32_e32 v111, v107
	v_mov_b32_e32 v112, v108
	v_mov_b32_e32 v113, v109
	v_permlane32_swap_b32_e32 v106, v110
	v_permlane32_swap_b32_e32 v107, v111
	v_permlane32_swap_b32_e32 v108, v112
	v_permlane32_swap_b32_e32 v109, v113
	v_add_f32_e32 v106, v106, v110
	v_add_f32_e32 v107, v107, v111
	v_add_f32_e32 v108, v108, v112
	v_add_f32_e32 v109, v109, v113
	v_mov_b32_e32 v110, v106
	v_mov_b32_e32 v111, v107
	v_mov_b32_e32 v112, v108
	v_mov_b32_e32 v113, v109
	v_permlane16_swap_b32_e32 v106, v110
	v_permlane16_swap_b32_e32 v107, v111
	v_permlane16_swap_b32_e32 v108, v112
	v_permlane16_swap_b32_e32 v109, v113
	v_add_f32_e32 v106, v106, v110
	v_add_f32_e32 v107, v107, v111
	v_add_f32_e32 v108, v108, v112
	v_add_f32_e32 v109, v109, v113
	v_add_f32_dpp v106, v106, v106 row_ror:8 row_mask:0xf bank_mask:0xf
	v_add_f32_dpp v107, v107, v107 row_ror:8 row_mask:0xf bank_mask:0xf
	v_add_f32_dpp v108, v108, v108 row_ror:8 row_mask:0xf bank_mask:0xf
	v_add_f32_dpp v109, v109, v109 row_ror:8 row_mask:0xf bank_mask:0xf
	v_add_f32_dpp v110, v106, v106 row_shl:4 row_mask:0xf bank_mask:0x5
	v_add_f32_dpp v111, v107, v107 row_shl:4 row_mask:0xf bank_mask:0x5
	v_add_f32_dpp v112, v108, v108 row_shl:4 row_mask:0xf bank_mask:0x5
	v_add_f32_dpp v113, v109, v109 row_shl:4 row_mask:0xf bank_mask:0x5
	v_add_f32_dpp v110, v106, v106 row_shr:4 row_mask:0xf bank_mask:0xa
	v_add_f32_dpp v111, v107, v107 row_shr:4 row_mask:0xf bank_mask:0xa
	v_add_f32_dpp v112, v108, v108 row_shr:4 row_mask:0xf bank_mask:0xa
	v_add_f32_dpp v113, v109, v109 row_shr:4 row_mask:0xf bank_mask:0xa
	v_add_f32_dpp v106, v110, v110 quad_perm:[2,3,0,1] row_mask:0xf bank_mask:0xf
	v_add_f32_dpp v107, v111, v111 quad_perm:[2,3,0,1] row_mask:0xf bank_mask:0xf
	v_add_f32_dpp v108, v112, v112 quad_perm:[2,3,0,1] row_mask:0xf bank_mask:0xf
	v_add_f32_dpp v109, v113, v113 quad_perm:[2,3,0,1] row_mask:0xf bank_mask:0xf
	v_add_f32_dpp v110, v106, v106 quad_perm:[1,0,3,2] row_mask:0xf bank_mask:0xf
	v_add_f32_dpp v111, v107, v107 quad_perm:[1,0,3,2] row_mask:0xf bank_mask:0xf
	v_add_f32_dpp v112, v108, v108 quad_perm:[1,0,3,2] row_mask:0xf bank_mask:0xf
	v_add_f32_dpp v113, v109, v109 quad_perm:[1,0,3,2] row_mask:0xf bank_mask:0xf
	v_fmamk_f32 v110, v110, 0x3a800000, v198
	v_fmamk_f32 v111, v111, 0x3a800000, v198
	v_fmamk_f32 v112, v112, 0x3a800000, v198
	v_fmamk_f32 v113, v113, 0x3a800000, v198
	v_rsq_f32_e32 v114, v110
	v_rsq_f32_e32 v116, v111
	v_rsq_f32_e32 v118, v112
	v_rsq_f32_e32 v120, v113
	ds_read_b128 v[140:143], v6 offset:4096
	ds_read_b128 v[144:147], v5 offset:20480
	ds_read_b128 v[122:125], v5 offset:40960
	s_waitcnt lgkmcnt(0)
	v_pk_add_f32 v[122:123], v[122:123], 1.0 op_sel_hi:[1,0]
	v_pk_add_f32 v[124:125], v[124:125], 1.0 op_sel_hi:[1,0]
	v_pk_mul_f32 v[10:11], v[10:11], v[114:115] op_sel_hi:[1,0]
	v_pk_mul_f32 v[12:13], v[12:13], v[114:115] op_sel_hi:[1,0]
	v_pk_mul_f32 v[10:11], v[140:141], v[10:11]
	v_pk_mul_f32 v[12:13], v[142:143], v[12:13]
	v_pk_fma_f32 v[10:11], v[122:123], v[10:11], v[144:145]
	v_pk_fma_f32 v[12:13], v[124:125], v[12:13], v[146:147]
	v_cvt_pk_bf16_f32 v10, v10, v11
	v_cvt_pk_bf16_f32 v11, v12, v13
	v_pk_mul_f32 v[26:27], v[26:27], v[116:117] op_sel_hi:[1,0]
	v_pk_mul_f32 v[28:29], v[28:29], v[116:117] op_sel_hi:[1,0]
	v_pk_mul_f32 v[26:27], v[140:141], v[26:27]
	v_pk_mul_f32 v[28:29], v[142:143], v[28:29]
	v_pk_fma_f32 v[26:27], v[122:123], v[26:27], v[144:145]
	v_pk_fma_f32 v[28:29], v[124:125], v[28:29], v[146:147]
	v_cvt_pk_bf16_f32 v26, v26, v27
	v_cvt_pk_bf16_f32 v27, v28, v29
	v_pk_mul_f32 v[42:43], v[42:43], v[118:119] op_sel_hi:[1,0]
	v_pk_mul_f32 v[44:45], v[44:45], v[118:119] op_sel_hi:[1,0]
	v_pk_mul_f32 v[42:43], v[140:141], v[42:43]
	v_pk_mul_f32 v[44:45], v[142:143], v[44:45]
	v_pk_fma_f32 v[42:43], v[122:123], v[42:43], v[144:145]
	v_pk_fma_f32 v[44:45], v[124:125], v[44:45], v[146:147]
	v_cvt_pk_bf16_f32 v42, v42, v43
	v_cvt_pk_bf16_f32 v43, v44, v45
	v_pk_mul_f32 v[58:59], v[58:59], v[120:121] op_sel_hi:[1,0]
	v_pk_mul_f32 v[60:61], v[60:61], v[120:121] op_sel_hi:[1,0]
	v_pk_mul_f32 v[58:59], v[140:141], v[58:59]
	v_pk_mul_f32 v[60:61], v[142:143], v[60:61]
	v_pk_fma_f32 v[58:59], v[122:123], v[58:59], v[144:145]
	v_pk_fma_f32 v[60:61], v[124:125], v[60:61], v[146:147]
	v_cvt_pk_bf16_f32 v58, v58, v59
	v_cvt_pk_bf16_f32 v59, v60, v61
	ds_read_b128 v[140:143], v6 offset:5120
	ds_read_b128 v[144:147], v5 offset:21504
	ds_read_b128 v[122:125], v5 offset:41984
	s_waitcnt lgkmcnt(0)
	v_pk_add_f32 v[122:123], v[122:123], 1.0 op_sel_hi:[1,0]
	v_pk_add_f32 v[124:125], v[124:125], 1.0 op_sel_hi:[1,0]
	v_pk_mul_f32 v[14:15], v[14:15], v[114:115] op_sel_hi:[1,0]
	v_pk_mul_f32 v[16:17], v[16:17], v[114:115] op_sel_hi:[1,0]
	v_pk_mul_f32 v[14:15], v[140:141], v[14:15]
	v_pk_mul_f32 v[16:17], v[142:143], v[16:17]
	v_pk_fma_f32 v[14:15], v[122:123], v[14:15], v[144:145]
	v_pk_fma_f32 v[16:17], v[124:125], v[16:17], v[146:147]
	v_cvt_pk_bf16_f32 v14, v14, v15
	v_cvt_pk_bf16_f32 v15, v16, v17
	v_pk_mul_f32 v[30:31], v[30:31], v[116:117] op_sel_hi:[1,0]
	v_pk_mul_f32 v[32:33], v[32:33], v[116:117] op_sel_hi:[1,0]
	v_pk_mul_f32 v[30:31], v[140:141], v[30:31]
	v_pk_mul_f32 v[32:33], v[142:143], v[32:33]
	v_pk_fma_f32 v[30:31], v[122:123], v[30:31], v[144:145]
	v_pk_fma_f32 v[32:33], v[124:125], v[32:33], v[146:147]
	v_cvt_pk_bf16_f32 v30, v30, v31
	v_cvt_pk_bf16_f32 v31, v32, v33
	v_pk_mul_f32 v[46:47], v[46:47], v[118:119] op_sel_hi:[1,0]
	v_pk_mul_f32 v[48:49], v[48:49], v[118:119] op_sel_hi:[1,0]
	v_pk_mul_f32 v[46:47], v[140:141], v[46:47]
	v_pk_mul_f32 v[48:49], v[142:143], v[48:49]
	v_pk_fma_f32 v[46:47], v[122:123], v[46:47], v[144:145]
	v_pk_fma_f32 v[48:49], v[124:125], v[48:49], v[146:147]
	v_cvt_pk_bf16_f32 v46, v46, v47
	v_cvt_pk_bf16_f32 v47, v48, v49
	v_pk_mul_f32 v[62:63], v[62:63], v[120:121] op_sel_hi:[1,0]
	v_pk_mul_f32 v[64:65], v[64:65], v[120:121] op_sel_hi:[1,0]
	v_pk_mul_f32 v[62:63], v[140:141], v[62:63]
	v_pk_mul_f32 v[64:65], v[142:143], v[64:65]
	v_pk_fma_f32 v[62:63], v[122:123], v[62:63], v[144:145]
	v_pk_fma_f32 v[64:65], v[124:125], v[64:65], v[146:147]
	v_cvt_pk_bf16_f32 v62, v62, v63
	v_cvt_pk_bf16_f32 v63, v64, v65
	ds_read_b128 v[140:143], v6 offset:6144
	ds_read_b128 v[144:147], v5 offset:22528
	ds_read_b128 v[122:125], v5 offset:43008
	s_waitcnt lgkmcnt(0)
	v_pk_add_f32 v[122:123], v[122:123], 1.0 op_sel_hi:[1,0]
	v_pk_add_f32 v[124:125], v[124:125], 1.0 op_sel_hi:[1,0]
	v_pk_mul_f32 v[18:19], v[18:19], v[114:115] op_sel_hi:[1,0]
	v_pk_mul_f32 v[20:21], v[20:21], v[114:115] op_sel_hi:[1,0]
	v_pk_mul_f32 v[18:19], v[140:141], v[18:19]
	v_pk_mul_f32 v[20:21], v[142:143], v[20:21]
	v_pk_fma_f32 v[18:19], v[122:123], v[18:19], v[144:145]
	v_pk_fma_f32 v[20:21], v[124:125], v[20:21], v[146:147]
	v_cvt_pk_bf16_f32 v18, v18, v19
	v_cvt_pk_bf16_f32 v19, v20, v21
	v_pk_mul_f32 v[34:35], v[34:35], v[116:117] op_sel_hi:[1,0]
	v_pk_mul_f32 v[36:37], v[36:37], v[116:117] op_sel_hi:[1,0]
	v_pk_mul_f32 v[34:35], v[140:141], v[34:35]
	v_pk_mul_f32 v[36:37], v[142:143], v[36:37]
	v_pk_fma_f32 v[34:35], v[122:123], v[34:35], v[144:145]
	v_pk_fma_f32 v[36:37], v[124:125], v[36:37], v[146:147]
	v_cvt_pk_bf16_f32 v34, v34, v35
	v_cvt_pk_bf16_f32 v35, v36, v37
	v_pk_mul_f32 v[50:51], v[50:51], v[118:119] op_sel_hi:[1,0]
	v_pk_mul_f32 v[52:53], v[52:53], v[118:119] op_sel_hi:[1,0]
	v_pk_mul_f32 v[50:51], v[140:141], v[50:51]
	v_pk_mul_f32 v[52:53], v[142:143], v[52:53]
	v_pk_fma_f32 v[50:51], v[122:123], v[50:51], v[144:145]
	v_pk_fma_f32 v[52:53], v[124:125], v[52:53], v[146:147]
	v_cvt_pk_bf16_f32 v50, v50, v51
	v_cvt_pk_bf16_f32 v51, v52, v53
	v_pk_mul_f32 v[66:67], v[66:67], v[120:121] op_sel_hi:[1,0]
	v_pk_mul_f32 v[68:69], v[68:69], v[120:121] op_sel_hi:[1,0]
	v_pk_mul_f32 v[66:67], v[140:141], v[66:67]
	v_pk_mul_f32 v[68:69], v[142:143], v[68:69]
	v_pk_fma_f32 v[66:67], v[122:123], v[66:67], v[144:145]
	v_pk_fma_f32 v[68:69], v[124:125], v[68:69], v[146:147]
	v_cvt_pk_bf16_f32 v66, v66, v67
	v_cvt_pk_bf16_f32 v67, v68, v69
	ds_read_b128 v[140:143], v6 offset:7168
	ds_read_b128 v[144:147], v5 offset:23552
	ds_read_b128 v[122:125], v5 offset:44032
	s_waitcnt lgkmcnt(0)
	v_pk_add_f32 v[122:123], v[122:123], 1.0 op_sel_hi:[1,0]
	v_pk_add_f32 v[124:125], v[124:125], 1.0 op_sel_hi:[1,0]
	v_pk_mul_f32 v[22:23], v[22:23], v[114:115] op_sel_hi:[1,0]
	v_pk_mul_f32 v[24:25], v[24:25], v[114:115] op_sel_hi:[1,0]
	v_pk_mul_f32 v[22:23], v[140:141], v[22:23]
	v_pk_mul_f32 v[24:25], v[142:143], v[24:25]
	v_pk_fma_f32 v[22:23], v[122:123], v[22:23], v[144:145]
	v_pk_fma_f32 v[24:25], v[124:125], v[24:25], v[146:147]
	v_cvt_pk_bf16_f32 v22, v22, v23
	v_cvt_pk_bf16_f32 v23, v24, v25
	v_pk_mul_f32 v[38:39], v[38:39], v[116:117] op_sel_hi:[1,0]
	v_pk_mul_f32 v[40:41], v[40:41], v[116:117] op_sel_hi:[1,0]
	v_pk_mul_f32 v[38:39], v[140:141], v[38:39]
	v_pk_mul_f32 v[40:41], v[142:143], v[40:41]
	v_pk_fma_f32 v[38:39], v[122:123], v[38:39], v[144:145]
	v_pk_fma_f32 v[40:41], v[124:125], v[40:41], v[146:147]
	v_cvt_pk_bf16_f32 v38, v38, v39
	v_cvt_pk_bf16_f32 v39, v40, v41
	v_pk_mul_f32 v[54:55], v[54:55], v[118:119] op_sel_hi:[1,0]
	v_pk_mul_f32 v[56:57], v[56:57], v[118:119] op_sel_hi:[1,0]
	v_pk_mul_f32 v[54:55], v[140:141], v[54:55]
	v_pk_mul_f32 v[56:57], v[142:143], v[56:57]
	v_pk_fma_f32 v[54:55], v[122:123], v[54:55], v[144:145]
	v_pk_fma_f32 v[56:57], v[124:125], v[56:57], v[146:147]
	v_cvt_pk_bf16_f32 v54, v54, v55
	v_cvt_pk_bf16_f32 v55, v56, v57
	v_pk_mul_f32 v[70:71], v[70:71], v[120:121] op_sel_hi:[1,0]
	v_pk_mul_f32 v[72:73], v[72:73], v[120:121] op_sel_hi:[1,0]
	v_pk_mul_f32 v[70:71], v[140:141], v[70:71]
	v_pk_mul_f32 v[72:73], v[142:143], v[72:73]
	v_pk_fma_f32 v[70:71], v[122:123], v[70:71], v[144:145]
	v_pk_fma_f32 v[72:73], v[124:125], v[72:73], v[146:147]
	v_cvt_pk_bf16_f32 v70, v70, v71
	v_cvt_pk_bf16_f32 v71, v72, v73
	global_store_dwordx2 v4, v[10:11], s[40:41]
	global_store_dwordx2 v4, v[14:15], s[40:41] offset:512
	global_store_dwordx2 v4, v[18:19], s[40:41] offset:1024
	global_store_dwordx2 v4, v[22:23], s[40:41] offset:1536
	s_add_u32 s40, s40, 0x800
	s_addc_u32 s41, s41, 0
	global_store_dwordx2 v4, v[26:27], s[40:41]
	global_store_dwordx2 v4, v[30:31], s[40:41] offset:512
	global_store_dwordx2 v4, v[34:35], s[40:41] offset:1024
	global_store_dwordx2 v4, v[38:39], s[40:41] offset:1536
	s_add_u32 s40, s40, 0x800
	s_addc_u32 s41, s41, 0
	global_store_dwordx2 v4, v[42:43], s[40:41]
	global_store_dwordx2 v4, v[46:47], s[40:41] offset:512
	global_store_dwordx2 v4, v[50:51], s[40:41] offset:1024
	global_store_dwordx2 v4, v[54:55], s[40:41] offset:1536
	s_add_u32 s40, s40, 0x800
	s_addc_u32 s41, s41, 0
	global_store_dwordx2 v4, v[58:59], s[40:41]
	global_store_dwordx2 v4, v[62:63], s[40:41] offset:512
	global_store_dwordx2 v4, v[66:67], s[40:41] offset:1024
	global_store_dwordx2 v4, v[70:71], s[40:41] offset:1536
